# stick-breaking loop: next-tile LDS-DMA issue moved behind the QK MFMAs (replaces the idle hazard nops) instead of at the loop top
# speedup vs baseline: 1.0064x; 1.0013x over previous
; __device__ __forceinline__ int crow(int r, int hi) { return (r & 3) + 8 * (r >> 2) + 4 * hi; }
; template <bool DRY> __device__ __forceinline__ void sb_unit(int b, int h, int qi, bf16_t* Pm, const bf16_t* VT) {
;     ...
;         sb_load(nxt, Pm, VT, tok0, (kt > 0 ? kt - 1 : 0) * 32, h, r32, hi);
;         f32x16 p = {};
; #pragma unroll
;         for (int s = 0; s < 4; ++s) p = __builtin_amdgcn_mfma_f32_32x32x16_bf16(cur.kf[s], qf[s], p, 0, 0, 0);
;         const bool diag = (kt == qi);
;         float lk[16], inner[16], Tg[4], TP[4], pre[4];
; #pragma unroll
;         for (int r = 0; r < 16; ++r) {
;             const float z = p[r] * 0.125f; p[r] = z;
;             const float e = __expf(-fabsf(z)); const float sp = fmaxf(z, 0.f) + __logf(1.f + e);
;             const bool valid = !diag || (crow(r, hi) < r32);
;             lk[r] = valid ? -sp : 0.f;
.Lsb_nostep_a:
.LBB0_742:
	s_xor_b32 s98, s98, 0x2000
	s_xor_b32 s99, s98, 0x2000
	v_add_u32_e32 v210, s99, v192
	v_add_u32_e32 v211, s99, v193
	v_add_u32_e32 v212, s99, v194
	v_add_u32_e32 v213, s99, v195
	v_add_u32_e32 v214, s99, v196
	v_add_u32_e32 v215, s99, v197
	v_add_u32_e32 v216, s99, v198
	v_add_u32_e32 v217, s99, v199
	s_waitcnt vmcnt(0)
	ds_read_b128 v[136:139], v210
	ds_read_b128 v[112:115], v211
	ds_read_b128 v[108:111], v212
	ds_read_b128 v[104:107], v213
	ds_read_b64 v[80:81], v214 offset:4096
	ds_read_b64 v[82:83], v215 offset:4096
	ds_read_b64 v[72:73], v216 offset:4096
	ds_read_b64 v[74:75], v217 offset:4096
	ds_read_b64 v[76:77], v214 offset:6144
	ds_read_b64 v[78:79], v215 offset:6144
	ds_read_b64 v[68:69], v216 offset:6144
	ds_read_b64 v[70:71], v217 offset:6144
	s_waitcnt lgkmcnt(8)
	v_mfma_f32_32x32x16_bf16 v[36:51], v[136:139], v[52:55], 0
	v_mfma_f32_32x32x16_bf16 v[36:51], v[112:115], v[56:59], v[36:51]
	v_mfma_f32_32x32x16_bf16 v[36:51], v[108:111], v[60:63], v[36:51]
	v_mfma_f32_32x32x16_bf16 v[36:51], v[104:107], v[64:67], v[36:51]
	s_add_i32 m0, s98, 0
	s_nop 0
	global_load_lds_dwordx4 v[172:173], off
	s_add_i32 m0, s98, 1024
	s_nop 0
	global_load_lds_dwordx4 v[174:175], off
	s_add_i32 m0, s98, 2048
	s_nop 0
	global_load_lds_dwordx4 v[176:177], off
	s_add_i32 m0, s98, 3072
	s_nop 0
	global_load_lds_dwordx4 v[178:179], off
	s_add_i32 m0, s98, 4096
	s_nop 0
	global_load_lds_dwordx4 v[180:181], off
	s_add_i32 m0, s98, 5120
	s_nop 0
	global_load_lds_dwordx4 v[182:183], off
	s_add_i32 m0, s98, 6144
	s_nop 0
	global_load_lds_dwordx4 v[184:185], off
	s_add_i32 m0, s98, 7168
	s_nop 0
	global_load_lds_dwordx4 v[186:187], off
	v_cmp_lt_i32_e32 vcc, 0, v100
	v_add_u32_e32 v100, -1, v100
	s_nop 0
	s_cbranch_vccz .Lsb_nostep_b
	v_lshl_add_u64 v[172:173], v[172:173], 0, v[188:189]
	v_lshl_add_u64 v[174:175], v[174:175], 0, v[188:189]
	v_lshl_add_u64 v[176:177], v[176:177], 0, v[188:189]
	v_lshl_add_u64 v[178:179], v[178:179], 0, v[188:189]
	v_lshl_add_u64 v[180:181], v[180:181], 0, v[190:191]
	v_lshl_add_u64 v[182:183], v[182:183], 0, v[190:191]
	v_lshl_add_u64 v[184:185], v[184:185], 0, v[190:191]
	v_lshl_add_u64 v[186:187], v[186:187], 0, v[190:191]
.Lsb_nostep_b:
	v_mul_f32_e32 v36, 0x3e38aa3b, v36
	v_mul_f32_e32 v37, 0x3e38aa3b, v37
	v_exp_f32_e64 v96, -|v36|
	v_exp_f32_e64 v97, -|v37|
	v_min_f32_e64 v104, -v36, 0
	v_min_f32_e64 v105, -v37, 0
	v_add_f32_e32 v96, 1.0, v96
	v_add_f32_e32 v97, 1.0, v97
	v_log_f32_e32 v96, v96
	v_log_f32_e32 v97, v97
	v_cndmask_b32_e64 v121, v102, 0, s[12:13]
	v_sub_f32_e32 v104, v104, v96
	v_sub_f32_e32 v105, v105, v97
	v_cndmask_b32_e64 v104, 0, v104, s[44:45]
	v_cndmask_b32_e64 v105, 0, v105, s[46:47]
	v_mul_f32_e32 v38, 0x3e38aa3b, v38
	v_mul_f32_e32 v39, 0x3e38aa3b, v39
	v_exp_f32_e64 v103, -|v38|
	v_exp_f32_e64 v120, -|v39|
	v_min_f32_e64 v106, -v38, 0
	v_min_f32_e64 v107, -v39, 0
	v_add_f32_e32 v103, 1.0, v103
	v_add_f32_e32 v120, 1.0, v120
	v_log_f32_e32 v103, v103
	v_log_f32_e32 v120, v120
	v_sub_f32_e32 v106, v106, v103
	v_sub_f32_e32 v107, v107, v120
	v_cndmask_b32_e64 v106, 0, v106, s[48:49]
	v_cndmask_b32_e64 v107, 0, v107, s[50:51]
	v_mul_f32_e32 v40, 0x3e38aa3b, v40
	v_mul_f32_e32 v41, 0x3e38aa3b, v41
	v_exp_f32_e64 v96, -|v40|
	v_exp_f32_e64 v97, -|v41|
	v_min_f32_e64 v108, -v40, 0
	v_min_f32_e64 v109, -v41, 0
	v_add_f32_e32 v96, 1.0, v96
	v_add_f32_e32 v97, 1.0, v97
	v_log_f32_e32 v96, v96
	v_log_f32_e32 v97, v97
	v_sub_f32_e32 v108, v108, v96
	v_sub_f32_e32 v109, v109, v97
	v_cndmask_b32_e64 v108, 0, v108, s[52:53]
	v_cndmask_b32_e64 v109, 0, v109, s[54:55]
	v_mul_f32_e32 v42, 0x3e38aa3b, v42
	v_mul_f32_e32 v43, 0x3e38aa3b, v43
	v_exp_f32_e64 v103, -|v42|
	v_exp_f32_e64 v120, -|v43|
	v_min_f32_e64 v110, -v42, 0
	v_min_f32_e64 v111, -v43, 0
	v_add_f32_e32 v103, 1.0, v103
	v_add_f32_e32 v120, 1.0, v120
	v_log_f32_e32 v103, v103
	v_log_f32_e32 v120, v120
	v_sub_f32_e32 v110, v110, v103
	v_sub_f32_e32 v111, v111, v120
	v_cndmask_b32_e64 v110, 0, v110, s[56:57]
	v_cndmask_b32_e64 v111, 0, v111, s[58:59]
	v_mul_f32_e32 v44, 0x3e38aa3b, v44
	v_mul_f32_e32 v45, 0x3e38aa3b, v45
	v_exp_f32_e64 v96, -|v44|
	v_exp_f32_e64 v97, -|v45|
	v_min_f32_e64 v112, -v44, 0
	v_min_f32_e64 v113, -v45, 0
	v_add_f32_e32 v96, 1.0, v96
	v_add_f32_e32 v97, 1.0, v97
	v_log_f32_e32 v96, v96
	v_log_f32_e32 v97, v97
	v_sub_f32_e32 v112, v112, v96
	v_sub_f32_e32 v113, v113, v97
	v_cndmask_b32_e64 v112, 0, v112, s[60:61]
	v_cndmask_b32_e64 v113, 0, v113, s[62:63]
	v_mul_f32_e32 v46, 0x3e38aa3b, v46
	v_mul_f32_e32 v47, 0x3e38aa3b, v47
	v_exp_f32_e64 v103, -|v46|
	v_exp_f32_e64 v120, -|v47|
	v_min_f32_e64 v114, -v46, 0
	v_min_f32_e64 v115, -v47, 0
	v_add_f32_e32 v103, 1.0, v103
	v_add_f32_e32 v120, 1.0, v120
	v_log_f32_e32 v103, v103
	v_log_f32_e32 v120, v120
	v_sub_f32_e32 v114, v114, v103
	v_sub_f32_e32 v115, v115, v120
	v_cndmask_b32_e64 v114, 0, v114, s[64:65]
	v_cndmask_b32_e64 v115, 0, v115, s[66:67]
	v_mul_f32_e32 v48, 0x3e38aa3b, v48
	v_mul_f32_e32 v49, 0x3e38aa3b, v49
	v_exp_f32_e64 v96, -|v48|
	v_exp_f32_e64 v97, -|v49|
	v_min_f32_e64 v116, -v48, 0
	v_min_f32_e64 v117, -v49, 0
	v_add_f32_e32 v96, 1.0, v96
	v_add_f32_e32 v97, 1.0, v97
	v_log_f32_e32 v96, v96
	v_log_f32_e32 v97, v97
	v_sub_f32_e32 v116, v116, v96
	v_sub_f32_e32 v117, v117, v97
	v_cndmask_b32_e64 v116, 0, v116, s[68:69]
	v_cndmask_b32_e64 v117, 0, v117, s[70:71]
	v_mul_f32_e32 v50, 0x3e38aa3b, v50
	v_mul_f32_e32 v51, 0x3e38aa3b, v51
	v_exp_f32_e64 v103, -|v50|
	v_exp_f32_e64 v120, -|v51|
	v_min_f32_e64 v118, -v50, 0
	v_min_f32_e64 v119, -v51, 0
	v_add_f32_e32 v103, 1.0, v103
	v_add_f32_e32 v120, 1.0, v120
	v_log_f32_e32 v103, v103
; __device__ __forceinline__ unsigned cvtpk(float lo, float hi) { f32x2_t v = {lo, hi}; bf16x2_t b = __builtin_convertvector(v, bf16x2_t); return __builtin_bit_cast(unsigned, b); }
; __device__ __forceinline__ int crow(int r, int hi) { return (r & 3) + 8 * (r >> 2) + 4 * hi; }
; template <bool DRY> __device__ __forceinline__ void sb_unit(int b, int h, int qi, bf16_t* Pm, const bf16_t* VT) {
;     ...
;             const float z = p[r] * 0.125f; p[r] = z;
;             const float e = __expf(-fabsf(z)); const float sp = fmaxf(z, 0.f) + __logf(1.f + e);
;             const bool valid = !diag || (crow(r, hi) < r32);
;             lk[r] = valid ? -sp : 0.f;
;         }
; #pragma unroll
;         for (int g = 0; g < 4; ++g) {
;             const float s3 = lk[4 * g + 3], s2 = s3 + lk[4 * g + 2], s1 = s2 + lk[4 * g + 1];
;             inner[4 * g + 3] = 0.f; inner[4 * g + 2] = s3; inner[4 * g + 1] = s2; inner[4 * g] = s1; Tg[g] = s1 + lk[4 * g];
;             TP[g] = __shfl_xor(Tg[g], 32);
;         }
;         float run = 0.f;
; #pragma unroll
;         for (int g = 3; g >= 0; --g) { pre[g] = run + (hi == 0 ? TP[g] : 0.f); run += Tg[g] + TP[g]; }
; #pragma unroll
;         for (int r = 0; r < 16; ++r) {
;             const bool valid = !diag || (crow(r, hi) < r32);
;             const float ex = fminf(p[r] + lk[r] + R + pre[r >> 2] + inner[r], 0.f);
;             p[r] = valid ? __expf(ex) : 0.f;
;         }
;         R += run;
; #pragma unroll
;         for (int s = 0; s < 2; ++s) {
;             const u32x4 pw = (u32x4){cvtpk(p[8 * s + 0], p[8 * s + 1]), cvtpk(p[8 * s + 2], p[8 * s + 3]), cvtpk(p[8 * s + 4], p[8 * s + 5]), cvtpk(p[8 * s + 6], p[8 * s + 7])};
;             const bf16x8 pf = __builtin_bit_cast(bf16x8, pw);
;             const s16x4 l0 = cur.v[4 * s], h0 = cur.v[4 * s + 1], l1 = cur.v[4 * s + 2], h1 = cur.v[4 * s + 3];
;             const bf16x8 v0 = (bf16x8){l0[0], l0[1], l0[2], l0[3], h0[0], h0[1], h0[2], h0[3]};
;             const bf16x8 v1 = (bf16x8){l1[0], l1[1], l1[2], l1[3], h1[0], h1[1], h1[2], h1[3]};
;             o0 = __builtin_amdgcn_mfma_f32_32x32x16_bf16(v0, pf, o0, 0, 0, 0);
;             o1 = __builtin_amdgcn_mfma_f32_32x32x16_bf16(v1, pf, o1, 0, 0, 0);
;         }
;         if (__all(R < -104.f)) break;
;         cur = nxt;
;     }
	v_log_f32_e32 v120, v120
	v_sub_f32_e32 v118, v118, v103
	v_sub_f32_e32 v119, v119, v120
	v_cndmask_b32_e64 v118, 0, v118, s[72:73]
	v_cndmask_b32_e64 v119, 0, v119, s[74:75]
	v_add_f32_e32 v106, v106, v107
	v_add_f32_e32 v110, v110, v111
	v_add_f32_e32 v114, v114, v115
	v_add_f32_e32 v118, v118, v119
	v_add_f32_e32 v105, v105, v106
	v_add_f32_e32 v109, v109, v110
	v_add_f32_e32 v113, v113, v114
	v_add_f32_e32 v117, v117, v118
	v_add_f32_e32 v104, v104, v105
	v_add_f32_e32 v108, v108, v109
	v_add_f32_e32 v112, v112, v113
	v_add_f32_e32 v116, v116, v117
	v_add_f32_e32 v122, v116, v121
	v_add_f32_e32 v36, v36, v104
	v_add_f32_e32 v37, v37, v105
	v_add_f32_e32 v38, v38, v106
	v_add_f32_e32 v39, v39, v107
	v_add_f32_e32 v123, v122, v112
	v_add_f32_e32 v40, v40, v108
	v_add_f32_e32 v41, v41, v109
	v_add_f32_e32 v42, v42, v110
	v_add_f32_e32 v43, v43, v111
	v_add_f32_e32 v124, v123, v108
	v_add_f32_e32 v44, v44, v112
	v_add_f32_e32 v45, v45, v113
	v_add_f32_e32 v46, v46, v114
	v_add_f32_e32 v47, v47, v115
	v_add_f32_e32 v125, v124, v104
	v_add_f32_e32 v48, v48, v116
	v_add_f32_e32 v49, v49, v117
	v_add_f32_e32 v50, v50, v118
	v_add_f32_e32 v51, v51, v119
	v_mov_b32_e32 v126, v122
	v_cndmask_b32_e64 v130, v121, v125, s[12:13]
	v_cndmask_b32_e64 v127, v123, v122, s[12:13]
	v_cndmask_b32_e64 v128, v124, v123, s[12:13]
	v_cndmask_b32_e64 v129, v125, v124, s[12:13]
	v_permlane32_swap_b32_e32 v126, v130
	v_permlane32_swap_b32_e32 v127, v122
	v_permlane32_swap_b32_e32 v128, v123
	v_permlane32_swap_b32_e32 v129, v124
	v_add_f32_e32 v102, v125, v126
	v_add_f32_e32 v127, v127, v122
	v_add_f32_e32 v128, v128, v123
	v_add_f32_e32 v129, v129, v124
	v_add_f32_e32 v48, v48, v130
	v_add_f32_e32 v49, v49, v130
	v_add_f32_e32 v50, v50, v130
	v_add_f32_e32 v51, v51, v130
	v_add_f32_e32 v44, v44, v127
	v_add_f32_e32 v45, v45, v127
	v_add_f32_e32 v46, v46, v127
	v_add_f32_e32 v47, v47, v127
	v_add_f32_e32 v40, v40, v128
	v_add_f32_e32 v41, v41, v128
	v_add_f32_e32 v42, v42, v128
	v_add_f32_e32 v43, v43, v128
	v_add_f32_e32 v36, v36, v129
	v_add_f32_e32 v37, v37, v129
	v_add_f32_e32 v38, v38, v129
	v_add_f32_e32 v39, v39, v129
	v_exp_f32_e64 v36, v36 clamp
	v_exp_f32_e64 v37, v37 clamp
	v_exp_f32_e64 v38, v38 clamp
	v_exp_f32_e64 v39, v39 clamp
	v_exp_f32_e64 v40, v40 clamp
	v_exp_f32_e64 v41, v41 clamp
	v_exp_f32_e64 v42, v42 clamp
	v_exp_f32_e64 v43, v43 clamp
	v_exp_f32_e64 v44, v44 clamp
	v_exp_f32_e64 v45, v45 clamp
	v_exp_f32_e64 v46, v46 clamp
	v_exp_f32_e64 v47, v47 clamp
	v_exp_f32_e64 v48, v48 clamp
	v_exp_f32_e64 v49, v49 clamp
	v_exp_f32_e64 v50, v50 clamp
	v_exp_f32_e64 v51, v51 clamp
	s_nop 0
	v_cndmask_b32_e64 v36, 0, v36, s[44:45]
	v_cndmask_b32_e64 v37, 0, v37, s[46:47]
	v_cndmask_b32_e64 v38, 0, v38, s[48:49]
	v_cndmask_b32_e64 v39, 0, v39, s[50:51]
	v_cndmask_b32_e64 v40, 0, v40, s[52:53]
	v_cndmask_b32_e64 v41, 0, v41, s[54:55]
	v_cndmask_b32_e64 v42, 0, v42, s[56:57]
	v_cndmask_b32_e64 v43, 0, v43, s[58:59]
	v_cndmask_b32_e64 v44, 0, v44, s[60:61]
	v_cndmask_b32_e64 v45, 0, v45, s[62:63]
	v_cndmask_b32_e64 v46, 0, v46, s[64:65]
	v_cndmask_b32_e64 v47, 0, v47, s[66:67]
	v_cndmask_b32_e64 v48, 0, v48, s[68:69]
	v_cndmask_b32_e64 v49, 0, v49, s[70:71]
	v_cndmask_b32_e64 v50, 0, v50, s[72:73]
	v_cndmask_b32_e64 v51, 0, v51, s[74:75]
	v_cvt_pk_bf16_f32 v36, v36, v37
	v_cvt_pk_bf16_f32 v37, v38, v39
	v_cvt_pk_bf16_f32 v38, v40, v41
	v_cvt_pk_bf16_f32 v39, v42, v43
	s_mov_b32 s4, 0xc3160a50
	v_cmp_gt_f32_e32 vcc, s4, v102
	s_waitcnt lgkmcnt(0)
	v_mfma_f32_32x32x16_bf16 v[4:19], v[80:83], v[36:39], v[4:19]
	v_cvt_pk_bf16_f32 v44, v44, v45
	v_cvt_pk_bf16_f32 v45, v46, v47
	v_mfma_f32_32x32x16_bf16 v[20:35], v[76:79], v[36:39], v[20:35]
	v_cvt_pk_bf16_f32 v46, v48, v49
	v_cvt_pk_bf16_f32 v47, v50, v51
	s_cmp_eq_u32 vcc_hi, exec_hi
	s_cselect_b64 s[4:5], -1, 0
	v_cmp_eq_u32_e32 vcc, s28, v98
	s_or_b64 s[4:5], s[4:5], vcc
	s_add_i32 s28, s28, 1
	s_and_b64 s[4:5], exec, s[4:5]
	s_or_b64 s[34:35], s[4:5], s[34:35]
	v_mfma_f32_32x32x16_bf16 v[4:19], v[72:75], v[44:47], v[4:19]
	v_mfma_f32_32x32x16_bf16 v[20:35], v[68:71], v[44:47], v[20:35]
	s_andn2_b64 exec, exec, s[34:35]
	s_cbranch_execz .Lsbl_exit
.Lsbl_loop:
	s_xor_b32 s98, s98, 0x2000
	s_xor_b32 s99, s98, 0x2000
	v_add_u32_e32 v210, s99, v192
	v_add_u32_e32 v211, s99, v193
	v_add_u32_e32 v212, s99, v194
	v_add_u32_e32 v213, s99, v195
	v_add_u32_e32 v214, s99, v196
	v_add_u32_e32 v215, s99, v197
	v_add_u32_e32 v216, s99, v198
	v_add_u32_e32 v217, s99, v199
	s_waitcnt vmcnt(0)
	ds_read_b128 v[136:139], v210
	ds_read_b128 v[112:115], v211
	ds_read_b128 v[108:111], v212
	ds_read_b128 v[104:107], v213
	ds_read_b64 v[80:81], v214 offset:4096
	ds_read_b64 v[82:83], v215 offset:4096
	ds_read_b64 v[72:73], v216 offset:4096
	ds_read_b64 v[74:75], v217 offset:4096
	ds_read_b64 v[76:77], v214 offset:6144
	ds_read_b64 v[78:79], v215 offset:6144
	ds_read_b64 v[68:69], v216 offset:6144
	ds_read_b64 v[70:71], v217 offset:6144
	s_waitcnt lgkmcnt(8)
	v_mfma_f32_32x32x16_bf16 v[36:51], v[136:139], v[52:55], 0
	v_mfma_f32_32x32x16_bf16 v[36:51], v[112:115], v[56:59], v[36:51]
	v_mfma_f32_32x32x16_bf16 v[36:51], v[108:111], v[60:63], v[36:51]
	v_mfma_f32_32x32x16_bf16 v[36:51], v[104:107], v[64:67], v[36:51]
	s_add_i32 m0, s98, 0
	s_nop 0
	global_load_lds_dwordx4 v[172:173], off
	s_add_i32 m0, s98, 1024
	s_nop 0
	global_load_lds_dwordx4 v[174:175], off
	s_add_i32 m0, s98, 2048
	s_nop 0
	global_load_lds_dwordx4 v[176:177], off
	s_add_i32 m0, s98, 3072
	s_nop 0
	global_load_lds_dwordx4 v[178:179], off
	s_add_i32 m0, s98, 4096
	s_nop 0
	global_load_lds_dwordx4 v[180:181], off
	s_add_i32 m0, s98, 5120
	s_nop 0
	global_load_lds_dwordx4 v[182:183], off
	s_add_i32 m0, s98, 6144
	s_nop 0
	global_load_lds_dwordx4 v[184:185], off
	s_add_i32 m0, s98, 7168
	s_nop 0
	global_load_lds_dwordx4 v[186:187], off
	v_cmp_lt_i32_e32 vcc, 0, v100
	v_add_u32_e32 v100, -1, v100
	s_nop 0
	s_cbranch_vccz .Lsb_nostep_c
	v_lshl_add_u64 v[172:173], v[172:173], 0, v[188:189]
	v_lshl_add_u64 v[174:175], v[174:175], 0, v[188:189]
	v_lshl_add_u64 v[176:177], v[176:177], 0, v[188:189]
	v_lshl_add_u64 v[178:179], v[178:179], 0, v[188:189]
	v_lshl_add_u64 v[180:181], v[180:181], 0, v[190:191]
	v_lshl_add_u64 v[182:183], v[182:183], 0, v[190:191]
	v_lshl_add_u64 v[184:185], v[184:185], 0, v[190:191]
	v_lshl_add_u64 v[186:187], v[186:187], 0, v[190:191]
; __device__ __forceinline__ int crow(int r, int hi) { return (r & 3) + 8 * (r >> 2) + 4 * hi; }
; template <bool DRY> __device__ __forceinline__ void sb_unit(int b, int h, int qi, bf16_t* Pm, const bf16_t* VT) {
;     ...
;         for (int s = 0; s < 4; ++s) p = __builtin_amdgcn_mfma_f32_32x32x16_bf16(cur.kf[s], qf[s], p, 0, 0, 0);
;         const bool diag = (kt == qi);
;         float lk[16], inner[16], Tg[4], TP[4], pre[4];
; #pragma unroll
;         for (int r = 0; r < 16; ++r) {
;             const float z = p[r] * 0.125f; p[r] = z;
;             const float e = __expf(-fabsf(z)); const float sp = fmaxf(z, 0.f) + __logf(1.f + e);
;             const bool valid = !diag || (crow(r, hi) < r32);
;             lk[r] = valid ? -sp : 0.f;
;         }
; #pragma unroll
;         for (int g = 0; g < 4; ++g) {
;             const float s3 = lk[4 * g + 3], s2 = s3 + lk[4 * g + 2], s1 = s2 + lk[4 * g + 1];
;             inner[4 * g + 3] = 0.f; inner[4 * g + 2] = s3; inner[4 * g + 1] = s2; inner[4 * g] = s1; Tg[g] = s1 + lk[4 * g];
;             TP[g] = __shfl_xor(Tg[g], 32);
;         }
;         float run = 0.f;
; #pragma unroll
;         for (int g = 3; g >= 0; --g) { pre[g] = run + (hi == 0 ? TP[g] : 0.f); run += Tg[g] + TP[g]; }
; #pragma unroll
;         for (int r = 0; r < 16; ++r) {
;             const bool valid = !diag || (crow(r, hi) < r32);
;             const float ex = fminf(p[r] + lk[r] + R + pre[r >> 2] + inner[r], 0.f);
;             p[r] = valid ? __expf(ex) : 0.f;
;         }
;         R += run;
; #pragma unroll
;         for (int s = 0; s < 2; ++s) {
;             const u32x4 pw = (u32x4){cvtpk(p[8 * s + 0], p[8 * s + 1]), cvtpk(p[8 * s + 2], p[8 * s + 3]), cvtpk(p[8 * s + 4], p[8 * s + 5]), cvtpk(p[8 * s + 6], p[8 * s + 7])};
;             const bf16x8 pf = __builtin_bit_cast(bf16x8, pw);
;             const s16x4 l0 = cur.v[4 * s], h0 = cur.v[4 * s + 1], l1 = cur.v[4 * s + 2], h1 = cur.v[4 * s + 3];
;             const bf16x8 v0 = (bf16x8){l0[0], l0[1], l0[2], l0[3], h0[0], h0[1], h0[2], h0[3]};
;             const bf16x8 v1 = (bf16x8){l1[0], l1[1], l1[2], l1[3], h1[0], h1[1], h1[2], h1[3]};
;             o0 = __builtin_amdgcn_mfma_f32_32x32x16_bf16(v0, pf, o0, 0, 0, 0);
;             o1 = __builtin_amdgcn_mfma_f32_32x32x16_bf16(v1, pf, o1, 0, 0, 0);
;         }
;         if (__all(R < -104.f)) break;
.Lsb_nostep_c:
	v_mul_f32_e32 v36, 0x3e38aa3b, v36
	v_mul_f32_e32 v37, 0x3e38aa3b, v37
	v_exp_f32_e64 v96, -|v36|
	v_exp_f32_e64 v97, -|v37|
	v_min_f32_e64 v104, -v36, 0
	v_min_f32_e64 v105, -v37, 0
	v_add_f32_e32 v96, 1.0, v96
	v_add_f32_e32 v97, 1.0, v97
	v_log_f32_e32 v96, v96
	v_log_f32_e32 v97, v97
	v_cndmask_b32_e64 v121, v102, 0, s[12:13]
	v_sub_f32_e32 v104, v104, v96
	v_sub_f32_e32 v105, v105, v97
	v_mul_f32_e32 v38, 0x3e38aa3b, v38
	v_mul_f32_e32 v39, 0x3e38aa3b, v39
	v_exp_f32_e64 v103, -|v38|
	v_exp_f32_e64 v120, -|v39|
	v_min_f32_e64 v106, -v38, 0
	v_min_f32_e64 v107, -v39, 0
	v_add_f32_e32 v103, 1.0, v103
	v_add_f32_e32 v120, 1.0, v120
	v_log_f32_e32 v103, v103
	v_log_f32_e32 v120, v120
	v_sub_f32_e32 v106, v106, v103
	v_sub_f32_e32 v107, v107, v120
	v_mul_f32_e32 v40, 0x3e38aa3b, v40
	v_mul_f32_e32 v41, 0x3e38aa3b, v41
	v_exp_f32_e64 v96, -|v40|
	v_exp_f32_e64 v97, -|v41|
	v_min_f32_e64 v108, -v40, 0
	v_min_f32_e64 v109, -v41, 0
	v_add_f32_e32 v96, 1.0, v96
	v_add_f32_e32 v97, 1.0, v97
	v_log_f32_e32 v96, v96
	v_log_f32_e32 v97, v97
	v_sub_f32_e32 v108, v108, v96
	v_sub_f32_e32 v109, v109, v97
	v_mul_f32_e32 v42, 0x3e38aa3b, v42
	v_mul_f32_e32 v43, 0x3e38aa3b, v43
	v_exp_f32_e64 v103, -|v42|
	v_exp_f32_e64 v120, -|v43|
	v_min_f32_e64 v110, -v42, 0
	v_min_f32_e64 v111, -v43, 0
	v_add_f32_e32 v103, 1.0, v103
	v_add_f32_e32 v120, 1.0, v120
	v_log_f32_e32 v103, v103
	v_log_f32_e32 v120, v120
	v_sub_f32_e32 v110, v110, v103
	v_sub_f32_e32 v111, v111, v120
	v_mul_f32_e32 v44, 0x3e38aa3b, v44
	v_mul_f32_e32 v45, 0x3e38aa3b, v45
	v_exp_f32_e64 v96, -|v44|
	v_exp_f32_e64 v97, -|v45|
	v_min_f32_e64 v112, -v44, 0
	v_min_f32_e64 v113, -v45, 0
	v_add_f32_e32 v96, 1.0, v96
	v_add_f32_e32 v97, 1.0, v97
	v_log_f32_e32 v96, v96
	v_log_f32_e32 v97, v97
	v_sub_f32_e32 v112, v112, v96
	v_sub_f32_e32 v113, v113, v97
	v_mul_f32_e32 v46, 0x3e38aa3b, v46
	v_mul_f32_e32 v47, 0x3e38aa3b, v47
	v_exp_f32_e64 v103, -|v46|
	v_exp_f32_e64 v120, -|v47|
	v_min_f32_e64 v114, -v46, 0
	v_min_f32_e64 v115, -v47, 0
	v_add_f32_e32 v103, 1.0, v103
	v_add_f32_e32 v120, 1.0, v120
	v_log_f32_e32 v103, v103
	v_log_f32_e32 v120, v120
	v_sub_f32_e32 v114, v114, v103
	v_sub_f32_e32 v115, v115, v120
	v_mul_f32_e32 v48, 0x3e38aa3b, v48
	v_mul_f32_e32 v49, 0x3e38aa3b, v49
	v_exp_f32_e64 v96, -|v48|
	v_exp_f32_e64 v97, -|v49|
	v_min_f32_e64 v116, -v48, 0
	v_min_f32_e64 v117, -v49, 0
	v_add_f32_e32 v96, 1.0, v96
	v_add_f32_e32 v97, 1.0, v97
	v_log_f32_e32 v96, v96
	v_log_f32_e32 v97, v97
	v_sub_f32_e32 v116, v116, v96
	v_sub_f32_e32 v117, v117, v97
	v_mul_f32_e32 v50, 0x3e38aa3b, v50
	v_mul_f32_e32 v51, 0x3e38aa3b, v51
	v_exp_f32_e64 v103, -|v50|
	v_exp_f32_e64 v120, -|v51|
	v_min_f32_e64 v118, -v50, 0
	v_min_f32_e64 v119, -v51, 0
	v_add_f32_e32 v103, 1.0, v103
	v_add_f32_e32 v120, 1.0, v120
	v_log_f32_e32 v103, v103
	v_log_f32_e32 v120, v120
	v_sub_f32_e32 v118, v118, v103
	v_sub_f32_e32 v119, v119, v120
	v_add_f32_e32 v106, v106, v107
	v_add_f32_e32 v110, v110, v111
	v_add_f32_e32 v114, v114, v115
	v_add_f32_e32 v118, v118, v119
	v_add_f32_e32 v105, v105, v106
	v_add_f32_e32 v109, v109, v110
	v_add_f32_e32 v113, v113, v114
	v_add_f32_e32 v117, v117, v118
	v_add_f32_e32 v104, v104, v105
	v_add_f32_e32 v108, v108, v109
	v_add_f32_e32 v112, v112, v113
	v_add_f32_e32 v116, v116, v117
	v_add_f32_e32 v122, v116, v121
	v_add_f32_e32 v36, v36, v104
	v_add_f32_e32 v37, v37, v105
	v_add_f32_e32 v38, v38, v106
	v_add_f32_e32 v39, v39, v107
	v_add_f32_e32 v123, v122, v112
	v_add_f32_e32 v40, v40, v108
	v_add_f32_e32 v41, v41, v109
	v_add_f32_e32 v42, v42, v110
	v_add_f32_e32 v43, v43, v111
	v_add_f32_e32 v124, v123, v108
	v_add_f32_e32 v44, v44, v112
	v_add_f32_e32 v45, v45, v113
	v_add_f32_e32 v46, v46, v114
	v_add_f32_e32 v47, v47, v115
	v_add_f32_e32 v125, v124, v104
	v_add_f32_e32 v48, v48, v116
	v_add_f32_e32 v49, v49, v117
	v_add_f32_e32 v50, v50, v118
	v_add_f32_e32 v51, v51, v119
	v_mov_b32_e32 v126, v122
	v_cndmask_b32_e64 v130, v121, v125, s[12:13]
	v_cndmask_b32_e64 v127, v123, v122, s[12:13]
	v_cndmask_b32_e64 v128, v124, v123, s[12:13]
	v_cndmask_b32_e64 v129, v125, v124, s[12:13]
	v_permlane32_swap_b32_e32 v126, v130
	v_permlane32_swap_b32_e32 v127, v122
	v_permlane32_swap_b32_e32 v128, v123
	v_permlane32_swap_b32_e32 v129, v124
	v_add_f32_e32 v102, v125, v126
	v_add_f32_e32 v127, v127, v122
	v_add_f32_e32 v128, v128, v123
	v_add_f32_e32 v129, v129, v124
	v_add_f32_e32 v48, v48, v130
	v_add_f32_e32 v49, v49, v130
	v_add_f32_e32 v50, v50, v130
	v_add_f32_e32 v51, v51, v130
	v_add_f32_e32 v44, v44, v127
	v_add_f32_e32 v45, v45, v127
	v_add_f32_e32 v46, v46, v127
	v_add_f32_e32 v47, v47, v127
	v_add_f32_e32 v40, v40, v128
	v_add_f32_e32 v41, v41, v128
	v_add_f32_e32 v42, v42, v128
	v_add_f32_e32 v43, v43, v128
	v_add_f32_e32 v36, v36, v129
	v_add_f32_e32 v37, v37, v129
	v_add_f32_e32 v38, v38, v129
	v_add_f32_e32 v39, v39, v129
	v_exp_f32_e64 v36, v36 clamp
	v_exp_f32_e64 v37, v37 clamp
	v_exp_f32_e64 v38, v38 clamp
	v_exp_f32_e64 v39, v39 clamp
	v_exp_f32_e64 v40, v40 clamp
	v_exp_f32_e64 v41, v41 clamp
	v_exp_f32_e64 v42, v42 clamp
	v_exp_f32_e64 v43, v43 clamp
	v_exp_f32_e64 v44, v44 clamp
	v_exp_f32_e64 v45, v45 clamp
	v_exp_f32_e64 v46, v46 clamp
	v_exp_f32_e64 v47, v47 clamp
	v_exp_f32_e64 v48, v48 clamp
	v_exp_f32_e64 v49, v49 clamp
	v_exp_f32_e64 v50, v50 clamp
	v_exp_f32_e64 v51, v51 clamp
	s_nop 0
	v_cvt_pk_bf16_f32 v36, v36, v37
	v_cvt_pk_bf16_f32 v37, v38, v39
	v_cvt_pk_bf16_f32 v38, v40, v41
	v_cvt_pk_bf16_f32 v39, v42, v43
	s_mov_b32 s4, 0xc3160a50
	v_cmp_gt_f32_e32 vcc, s4, v102
	s_waitcnt lgkmcnt(0)
	v_mfma_f32_32x32x16_bf16 v[4:19], v[80:83], v[36:39], v[4:19]
	v_cvt_pk_bf16_f32 v44, v44, v45
	v_cvt_pk_bf16_f32 v45, v46, v47
	v_mfma_f32_32x32x16_bf16 v[20:35], v[76:79], v[36:39], v[20:35]
	v_cvt_pk_bf16_f32 v46, v48, v49
	v_cvt_pk_bf16_f32 v47, v50, v51
	s_cmp_eq_u32 vcc_hi, exec_hi
	s_cselect_b64 s[4:5], -1, 0
	v_cmp_eq_u32_e32 vcc, s28, v98
	s_or_b64 s[4:5], s[4:5], vcc
	s_add_i32 s28, s28, 1
	s_and_b64 s[4:5], exec, s[4:5]
	s_or_b64 s[34:35], s[4:5], s[34:35]
	v_mfma_f32_32x32x16_bf16 v[4:19], v[72:75], v[44:47], v[4:19]
	v_mfma_f32_32x32x16_bf16 v[20:35], v[68:71], v[44:47], v[20:35]
	s_andn2_b64 exec, exec, s[34:35]
	s_cbranch_execnz .Lsbl_loop
